# grid barriers (17 of 19): L1 invalidate issued by wave 1 at arrival, overlapping the wait, instead of after the release
# speedup vs baseline: 1.0118x; 1.0118x over previous
; __device__ __forceinline__ void xcd_barrier(const XcdBarrier& b) {
;     asm volatile("s_waitcnt vmcnt(0)" ::: "memory");
;     __syncthreads();
;     if (threadIdx.x == 0) {
;         unsigned* bar = b.bar;
;         __builtin_amdgcn_s_waitcnt(0);
;         unsigned nloc = b.st[0], nx = b.st[1];
;         if (nloc == 0u) { xcd_barrier_complete(bar, b.x, nloc, nx); b.st[0] = nloc; b.st[1] = nx; }
.LBB0_363:
	s_waitcnt vmcnt(0)
	s_waitcnt vmcnt(0) lgkmcnt(0)
	s_barrier
	s_mov_b64 s[4:5], exec
	v_readfirstlane_b32 s98, v254
	s_nop 0
	s_cmpk_lg_u32 s98, 0x40
	s_cbranch_scc1 .Learlyinv_2
	buffer_inv sc1
.Learlyinv_2:
	v_readlane_b32 s6, v255, 0
	v_readlane_b32 s7, v255, 1
	s_and_b64 s[6:7], s[4:5], s[6:7]
	s_mov_b64 exec, s[6:7]
	s_cbranch_execz .LBB0_411
	v_mov_b32_e32 v0, s74
	s_waitcnt vmcnt(0) expcnt(0) lgkmcnt(0)
	ds_read_b32 v2, v0
	ds_read_b32 v0, v0 offset:4
	s_waitcnt lgkmcnt(1)
	v_cmp_ne_u32_e32 vcc, 0, v2
	s_cbranch_vccnz .LBB0_379
	s_mov_b32 s3, 1
	v_mov_b32_e32 v16, 0
	s_branch .LBB0_367

; __device__ __forceinline__ unsigned xb_ld(unsigned* p)              { return __hip_atomic_load(p, __ATOMIC_RELAXED, __HIP_MEMORY_SCOPE_AGENT); }
; #define XB_SPIN(cond, bar) do { unsigned _sp = 0; while (cond) { __builtin_amdgcn_s_sleep(0); \
;     if ((++_sp & 255u) == 0u) { if (xb_ld(&(bar)[XB_TMO])) break; if (_sp > XB_SPIN_CAP) { atomicAdd(&(bar)[XB_TMO], 1u); break; } } } } while (0)
; __device__ __forceinline__ void xcd_barrier(const XcdBarrier& b) {
;     ...
;         } else {
;             XB_SPIN(xb_ld(&bar[XB_XGEN(b.x)]) == gen, bar);
;             __builtin_amdgcn_fence(__ATOMIC_ACQUIRE, "agent");
;             asm volatile("s_waitcnt vmcnt(0)" ::: "memory");
;         }
.LBB0_392:
	s_or_b64 exec, exec, s[10:11]
	s_waitcnt vmcnt(0)
	s_waitcnt vmcnt(0)

; __device__ __forceinline__ unsigned xb_ld(unsigned* p)              { return __hip_atomic_load(p, __ATOMIC_RELAXED, __HIP_MEMORY_SCOPE_AGENT); }
; __device__ __forceinline__ unsigned xb_add(unsigned* p, unsigned v) { return __hip_atomic_fetch_add(p, v, __ATOMIC_RELAXED, __HIP_MEMORY_SCOPE_AGENT); }
; #define XB_SPIN(cond, bar) do { unsigned _sp = 0; while (cond) { __builtin_amdgcn_s_sleep(0); \
;     if ((++_sp & 255u) == 0u) { if (xb_ld(&(bar)[XB_TMO])) break; if (_sp > XB_SPIN_CAP) { atomicAdd(&(bar)[XB_TMO], 1u); break; } } } } while (0)
; __device__ __forceinline__ void xcd_barrier(const XcdBarrier& b) {
;     ...
;             __builtin_amdgcn_fence(__ATOMIC_ACQUIRE, "agent");
;             xb_add(&bar[XB_XGEN(b.x)], 1u);
;             asm volatile("s_waitcnt vmcnt(0)" ::: "memory");
;         } else {
;             XB_SPIN(xb_ld(&bar[XB_XGEN(b.x)]) == gen, bar);
;             __builtin_amdgcn_fence(__ATOMIC_ACQUIRE, "agent");
;             asm volatile("s_waitcnt vmcnt(0)" ::: "memory");
;         }
;     }
;     __syncthreads();
.LBB0_410:
	s_or_b64 exec, exec, s[6:7]
	v_readlane_b32 s6, v255, 46
	v_mov_b32_e32 v0, 0
	v_mov_b32_e32 v1, 1
	v_readlane_b32 s7, v255, 47
	s_waitcnt vmcnt(0)
	s_nop 2
	global_atomic_add v0, v1, s[6:7]
	s_waitcnt vmcnt(0)
.LBB0_411:
	s_or_b64 exec, exec, s[4:5]
	s_waitcnt vmcnt(0) lgkmcnt(0)
	s_barrier

; __device__ __forceinline__ void xcd_barrier(const XcdBarrier& b) {
;     asm volatile("s_waitcnt vmcnt(0)" ::: "memory");
;     __syncthreads();
;     if (threadIdx.x == 0) {
.LBB0_576:
	s_cmp_lt_i32 s95, 6
	s_cbranch_scc1 .LBB0_626
	s_waitcnt vmcnt(0)
	s_waitcnt vmcnt(0) lgkmcnt(0)
	s_barrier
	s_mov_b64 s[4:5], exec
	v_readfirstlane_b32 s98, v254
	s_nop 0
	s_cmpk_lg_u32 s98, 0x40
	s_cbranch_scc1 .Learlyinv_4
	buffer_inv sc1

; __device__ __forceinline__ void xcd_barrier(const XcdBarrier& b) {
;     asm volatile("s_waitcnt vmcnt(0)" ::: "memory");
;     __syncthreads();
;     if (threadIdx.x == 0) {
.LBB0_659:
	s_cmp_lt_i32 s95, 7
	s_cbranch_scc1 .LBB0_709
	s_waitcnt vmcnt(0)
	s_waitcnt vmcnt(0)
	s_barrier
	s_mov_b64 s[4:5], exec
	v_readfirstlane_b32 s98, v254
	s_nop 0
	s_cmpk_lg_u32 s98, 0x40
	s_cbranch_scc1 .Learlyinv_5
	buffer_inv sc1

; __device__ __forceinline__ void xcd_barrier(const XcdBarrier& b) {
;     asm volatile("s_waitcnt vmcnt(0)" ::: "memory");
;     __syncthreads();
;     if (threadIdx.x == 0) {
.LBB0_867:
	s_cmp_lt_i32 s95, 8
	s_cbranch_scc1 .LBB0_917
	s_waitcnt vmcnt(0)
	s_barrier
	s_mov_b64 s[4:5], exec
	v_readfirstlane_b32 s98, v254
	s_nop 0
	s_cmpk_lg_u32 s98, 0x40
	s_cbranch_scc1 .Learlyinv_6
	buffer_inv sc1

; __device__ __forceinline__ void xcd_barrier(const XcdBarrier& b) {
;     asm volatile("s_waitcnt vmcnt(0)" ::: "memory");
;     __syncthreads();
;     if (threadIdx.x == 0) {
.LBB0_1264:
	s_cmp_lt_i32 s95, 11
	s_cbranch_scc1 .LBB0_1314
	s_waitcnt vmcnt(0)
	s_waitcnt vmcnt(0) lgkmcnt(0)
	s_barrier
	s_mov_b64 s[4:5], exec
	v_readfirstlane_b32 s98, v254
	s_nop 0
	s_cmpk_lg_u32 s98, 0x40
	s_cbranch_scc1 .Learlyinv_9
	buffer_inv sc1

; __device__ __forceinline__ void xcd_barrier(const XcdBarrier& b) {
;     asm volatile("s_waitcnt vmcnt(0)" ::: "memory");
;     __syncthreads();
;     if (threadIdx.x == 0) {
.LBB0_1462:
	s_cmp_lt_i32 s95, 13
	s_cbranch_scc1 .LBB0_1512
	s_waitcnt vmcnt(0)
	s_waitcnt vmcnt(0) lgkmcnt(0)
	s_barrier
	s_mov_b64 s[4:5], exec
	v_readfirstlane_b32 s98, v254
	s_nop 0
	s_cmpk_lg_u32 s98, 0x40
	s_cbranch_scc1 .Learlyinv_11
	buffer_inv sc1

; __device__ __forceinline__ void xcd_barrier(const XcdBarrier& b) {
;     asm volatile("s_waitcnt vmcnt(0)" ::: "memory");
;     __syncthreads();
;     if (threadIdx.x == 0) {
.LBB0_1530:
	s_cmp_lt_i32 s95, 14
	s_cbranch_scc1 .LBB0_1580
	s_waitcnt vmcnt(0)
	s_waitcnt vmcnt(0) lgkmcnt(0)
	s_barrier
	s_mov_b64 s[4:5], exec
	v_readfirstlane_b32 s98, v254
	s_nop 0
	s_cmpk_lg_u32 s98, 0x40
	s_cbranch_scc1 .Learlyinv_12
	buffer_inv sc1

; __device__ __forceinline__ void xcd_barrier(const XcdBarrier& b) {
;     asm volatile("s_waitcnt vmcnt(0)" ::: "memory");
;     __syncthreads();
;     if (threadIdx.x == 0) {
.LBB0_1702:
	s_cmp_lt_i32 s95, 16
	s_cbranch_scc1 .LBB0_1752
	s_waitcnt vmcnt(0)
	s_waitcnt vmcnt(0) lgkmcnt(0)
	s_barrier
	s_mov_b64 s[4:5], exec
	v_readfirstlane_b32 s98, v254
	s_nop 0
	s_cmpk_lg_u32 s98, 0x40
	s_cbranch_scc1 .Learlyinv_14
	buffer_inv sc1

; __device__ __forceinline__ void xcd_barrier(const XcdBarrier& b) {
;     asm volatile("s_waitcnt vmcnt(0)" ::: "memory");
;     __syncthreads();
;     if (threadIdx.x == 0) {
.LBB0_1835:
	s_cmp_lt_i32 s95, 17
	s_cbranch_scc1 .LBB0_1885
	s_waitcnt vmcnt(0)
	s_waitcnt vmcnt(0) lgkmcnt(0)
	s_barrier
	s_mov_b64 s[4:5], exec
	v_readfirstlane_b32 s98, v254
	s_nop 0
	s_cmpk_lg_u32 s98, 0x40
	s_cbranch_scc1 .Learlyinv_15
	buffer_inv sc1

; __device__ __forceinline__ void xcd_barrier(const XcdBarrier& b) {
;     asm volatile("s_waitcnt vmcnt(0)" ::: "memory");
;     __syncthreads();
;     if (threadIdx.x == 0) {
.LBB0_1999:
	s_cmp_lt_i32 s95, 19
	s_cbranch_scc1 .LBB0_2049
	s_waitcnt vmcnt(0)
	s_waitcnt vmcnt(0) lgkmcnt(0)
	s_barrier
	s_mov_b64 s[4:5], exec
	v_readfirstlane_b32 s98, v254
	s_nop 0
	s_cmpk_lg_u32 s98, 0x40
	s_cbranch_scc1 .Learlyinv_17
	buffer_inv sc1
